# v23 + HGRN pass 2 chunk loop: each pair of 2-byte token loads replaced by one dword load per lane plus quad_perm exchange and v_perm_b32 (24 VMEM instructions per wave-chunk instead of 48)
# baseline (speedup 1.0000x reference)
; #define LAS __attribute__((address_space(3)))
; template <bool FULL>
; __device__ __forceinline__ void hgrn_pass(int wv, const Args& a, int l, LAS unsigned char* lds, int item, bool dmy) {
;     ...
;     const int b = item >> 6, h = (item >> 3) & 7, p = item & 7;
;     const size_t row_base = (size_t)b * SEQ + (size_t)p * 1024;
;     const bf16_t* HQ = (const bf16_t*)(a.ws + WS_HQ); const bf16_t* HF = (const bf16_t*)(a.ws + WS_HF); const bf16_t* HI = (const bf16_t*)(a.ws + WS_HI); const bf16_t* HGt = (const bf16_t*)(a.ws + WS_HG);
;     bf16_t* OA = dmy ? (bf16_t*)(a.ws + WS_DUMMY) - (size_t)(b * SEQ + p * 1024) * DM : (bf16_t*)a.out;
;     float* US = (float*)(a.ws + WS_US); float* DT = (float*)(a.ws + WS_DT);
;     float lb = 0.f;
;     if (l == 1) { const float l0 = a.in[6][h * 128 + ch], l1 = a.in[6][DM + h * 128 + ch]; lb = 1.f / (1.f + expf(l0 - l1)); }
;     const float oml = 1.f - lb;
;     LAS float* TOT = (LAS float*)(lds + HG_TOT); LAS float* DV = (LAS float*)(lds + HG_DV); LAS float* SSQP = (LAS float*)(lds + HG_SSQP); LAS float* EM = (LAS float*)(lds + HG_EM);
;     const int ti = wid & 3, dvh = wid >> 2;
;     f32x4 sacc[8];
; #pragma unroll
;     for (int j = 0; j < 8; ++j) sacc[j] = (f32x4){0.f, 0.f, 0.f, 0.f};
;     float gsum = 0.f;
;     if (FULL) {
;         for (int pp = 0; pp < p; ++pp) {
;             const int it2 = item - p + pp;
;             const f32x4 dd = *(const f32x4*)(DT + (size_t)it2 * 128 + wid * 16 + 4 * fq);
; #pragma unroll
;             for (int j = 0; j < 8; ++j)
; #pragma unroll
;                 for (int r = 0; r < 4; ++r) sacc[j][r] = sacc[j][r] * dd[r] + US[((size_t)it2 * 128 + wid * 16 + 4 * fq + r) * 128 + j * 16 + fr];
;         }
;     }
;     const unsigned gcol = (unsigned)(h * 128 + ch);
;     unsigned cHF[8], cHI[8], cHQ[8];
;     ...
;     HG_LOAD(cHF, cHI, cHQ, 0);
.LBB0_473:
	s_ashr_i32 s9, s10, 7
	s_waitcnt lgkmcnt(0)
	s_add_u32 s40, s26, 0xc100000
	s_addc_u32 s41, s27, 0
	s_add_u32 s42, s26, 0x10100000
	s_addc_u32 s43, s27, 0
	s_add_u32 s45, s26, 0x14100000
	s_addc_u32 s46, s27, 0
	s_lshl_b32 s7, s9, 4
	s_ashr_i32 s0, s7, 31
	v_readlane_b32 s52, v253, 9
	v_readlane_b32 s53, v253, 10
	s_add_u32 s28, s52, s7
	s_addc_u32 s29, s53, s0
	s_lshl_b64 s[4:5], s[28:29], 11
	s_add_u32 s0, s42, s4
	s_addc_u32 s1, s43, s5
	s_add_u32 s2, s45, s4
	s_addc_u32 s3, s46, s5
	s_add_u32 s4, s40, s4
	s_addc_u32 s5, s41, s5
	s_add_u32 s12, s0, 0x1000
	s_addc_u32 s13, s1, 0
	s_add_u32 s14, s2, 0x1000
	s_addc_u32 s15, s3, 0
	s_add_u32 s16, s4, 0x1000
	s_addc_u32 s17, s5, 0
	s_add_u32 s18, s0, 0x2000
	s_addc_u32 s19, s1, 0
	s_add_u32 s20, s2, 0x2000
	s_addc_u32 s21, s3, 0
	v_or_b32_e32 v46, 0x400, v40
	s_add_u32 s22, s4, 0x2000
	v_lshlrev_b32_e32 v32, 1, v40
	v_lshlrev_b32_e32 v33, 1, v46
	s_addc_u32 s23, s5, 0
	global_load_ushort v34, v32, s[0:1]
	global_load_ushort v35, v32, s[0:1] offset:2048
	global_load_ushort v36, v32, s[2:3]
	global_load_ushort v37, v32, s[2:3] offset:2048
	global_load_ushort v38, v32, s[4:5]
	global_load_ushort v39, v32, s[4:5] offset:2048
	global_load_ushort v43, v32, s[12:13]
	global_load_ushort v50, v32, s[14:15]
	global_load_ushort v51, v33, s[12:13]
	global_load_ushort v52, v33, s[14:15]
	global_load_ushort v53, v33, s[16:17]
	global_load_ushort v54, v33, s[18:19]
	global_load_ushort v55, v33, s[20:21]
	s_add_u32 s12, s0, 0x3000
	s_addc_u32 s13, s1, 0
	s_add_u32 s14, s2, 0x3000
	s_addc_u32 s15, s3, 0
	s_add_u32 s36, s4, 0x3000
	s_addc_u32 s37, s5, 0
	s_add_u32 s38, s0, 0x4000
	s_addc_u32 s39, s1, 0
	s_add_u32 s48, s2, 0x4000
	s_addc_u32 s49, s3, 0
	s_add_u32 s50, s4, 0x4000
	s_addc_u32 s51, s5, 0
	global_load_ushort v56, v32, s[16:17]
	global_load_ushort v57, v32, s[18:19]
	global_load_ushort v58, v32, s[20:21]
	global_load_ushort v59, v32, s[22:23]
	global_load_ushort v60, v32, s[12:13]
	global_load_ushort v61, v32, s[14:15]
	global_load_ushort v62, v32, s[36:37]
	global_load_ushort v63, v32, s[38:39]
	s_add_u32 s16, s0, 0x5000
	s_addc_u32 s17, s1, 0
	s_add_u32 s18, s2, 0x5000
	s_addc_u32 s19, s3, 0
	s_add_u32 s20, s4, 0x5000
	s_addc_u32 s21, s5, 0
	global_load_ushort v64, v33, s[22:23]
	global_load_ushort v65, v33, s[12:13]
	global_load_ushort v66, v33, s[14:15]
	global_load_ushort v67, v33, s[36:37]
	global_load_ushort v68, v33, s[38:39]
	global_load_ushort v69, v33, s[48:49]
	global_load_ushort v70, v33, s[50:51]
	global_load_ushort v71, v33, s[16:17]
	s_add_u32 s12, s0, 0x6000
	s_addc_u32 s13, s1, 0
	s_add_u32 s14, s2, 0x6000
	s_addc_u32 s15, s3, 0
	s_add_u32 s22, s4, 0x6000
	s_addc_u32 s23, s5, 0
	s_add_u32 s0, s0, 0x7000
	s_addc_u32 s1, s1, 0
	global_load_ushort v73, v32, s[48:49]
	global_load_ushort v74, v32, s[50:51]
	global_load_ushort v75, v32, s[16:17]
	global_load_ushort v76, v32, s[18:19]
	global_load_ushort v77, v32, s[20:21]
	global_load_ushort v78, v32, s[12:13]
	global_load_ushort v79, v32, s[14:15]
	global_load_ushort v80, v32, s[22:23]
	s_add_u32 s2, s2, 0x7000
	s_addc_u32 s3, s3, 0
	s_add_u32 s4, s4, 0x7000
	s_addc_u32 s5, s5, 0
	global_load_ushort v81, v32, s[0:1]
	global_load_ushort v82, v32, s[2:3]
	global_load_ushort v83, v32, s[4:5]
	global_load_ushort v84, v33, s[18:19]
	global_load_ushort v85, v33, s[20:21]
	global_load_ushort v86, v33, s[12:13]
	global_load_ushort v87, v33, s[14:15]
	global_load_ushort v89, v33, s[22:23]
	global_load_ushort v90, v33, s[0:1]
	global_load_ushort v91, v33, s[2:3]
	global_load_ushort v92, v33, s[4:5]
	s_and_b32 s0, s10, 0x3fffff80
	s_lshl_b32 s0, s0, 2
	s_add_i32 s0, s69, s0
	v_lshlrev_b32_e32 v96, 2, v41
	s_cmp_gt_i32 s9, 0
	v_lshlrev_b32_e32 v48, 2, v48
	s_movk_i32 s49, 0x88
	v_readlane_b32 s13, v253, 24
	v_sub_f32_e32 v72, 1.0, v88
	s_mov_b32 s47, 64
	v_add_u32_e32 v95, 0, v96
	v_lshlrev_b32_e32 v117, 1, v40
	v_and_b32_e32 v118, 2, v117
	v_lshlrev_b32_e32 v118, 10, v118
	v_and_or_b32 v117, v117, -4, v118
	v_and_b32_e32 v118, 1, v40
	v_sub_u32_e32 v118, 0, v118
	v_and_b32_e32 v118, 0x6060606, v118
	v_xor_b32_e32 v118, 0x5040100, v118
	s_waitcnt vmcnt(46)
	v_lshl_or_b32 v228, v35, 16, v34
	s_waitcnt vmcnt(44)
	v_lshl_or_b32 v32, v37, 16, v36
	s_waitcnt vmcnt(42)
	v_lshl_or_b32 v181, v39, 16, v38
	s_waitcnt vmcnt(39)
	v_lshl_or_b32 v223, v51, 16, v43
	s_waitcnt vmcnt(38)
	v_lshl_or_b32 v33, v52, 16, v50
	v_mul_u32_u24_e32 v50, 0x48, v41
	v_add_u32_e32 v43, 0x88, v41
	v_or_b32_e32 v52, s7, v47
	v_mul_lo_u32 v52, v52, s49
	s_waitcnt vmcnt(34)
	v_lshl_or_b32 v180, v53, 16, v56
	s_waitcnt vmcnt(33)
	v_lshl_or_b32 v222, v54, 16, v57
	v_lshlrev_b32_e32 v53, 3, v49
	v_or_b32_e32 v54, s7, v42
	s_waitcnt vmcnt(32)
	v_lshl_or_b32 v34, v55, 16, v58
	v_mul_lo_u32 v58, v54, s55
	v_or_b32_e32 v55, 1, v54
	s_waitcnt vmcnt(26)
	v_lshl_or_b32 v179, v64, 16, v59
	s_waitcnt vmcnt(25)
	v_lshl_or_b32 v236, v65, 16, v60
	v_bfrev_b32_e32 v65, 0.5
	v_bitop3_b32 v93, v48, s54, v65 bitop3:0x6c
	s_waitcnt vmcnt(22)
	v_lshl_or_b32 v242, v68, 16, v63
	v_lshl_or_b32 v178, v67, 16, v62
	v_lshl_or_b32 v35, v66, 16, v61
	v_or_b32_e32 v56, 2, v54
	v_or_b32_e32 v57, 3, v54
	s_waitcnt vmcnt(18)
	v_lshl_or_b32 v36, v69, 16, v73
	s_waitcnt vmcnt(17)
	v_lshl_or_b32 v177, v70, 16, v74
	s_waitcnt vmcnt(16)
	v_lshl_or_b32 v199, v71, 16, v75
	v_add_u32_e32 v59, 0x48, v58
	v_add_u32_e32 v60, 0x90, v58
	s_waitcnt vmcnt(7)
	v_lshl_or_b32 v37, v84, 16, v76
	s_waitcnt vmcnt(6)
	v_lshl_or_b32 v176, v85, 16, v77
	v_add_u32_e32 v61, 0xd8, v58
	s_waitcnt vmcnt(4)
	v_lshl_or_b32 v38, v87, 16, v79
	s_waitcnt vmcnt(3)
; #define LAS __attribute__((address_space(3)))
; template <bool FULL>
; __device__ __forceinline__ void hgrn_pass(int wv, const Args& a, int l, LAS unsigned char* lds, int item, bool dmy) {
;     ...
;                 const int tiA = wid >> 1;
; #pragma unroll
;                 for (int q = 0; q < 2; ++q) {
;                     const int sj = (wid & 1) * 2 + q;
;                     f32x4 ac = (f32x4){0.f, 0.f, 0.f, 0.f};
; #pragma unroll
;                     for (int k4 = 0; k4 < 4; ++k4) {
;                         const bf16x8 av = lds_ld16(lds + HG_QH + ((tiA * 16 + fr) * 136 + k4 * 32 + 8 * fq) * 2);
;                         const bf16x8 bv = lds_ld16(lds + HG_KH + ((sj * 16 + fr) * 136 + k4 * 32 + 8 * fq) * 2);
;                         ac = mfma16(av, bv, ac);
;                     }
;                     const int s = sj * 16 + fr, tb0 = tiA * 16 + 4 * fq;
;                     const unsigned w0 = pk2(s <= tb0 ? ac[0] : 0.f, s <= tb0 + 1 ? ac[1] : 0.f), w1 = pk2(s <= tb0 + 2 ? ac[2] : 0.f, s <= tb0 + 3 ? ac[3] : 0.f);
;                     *(LAS bf16_t*)(lds + HG_AM + ((tb0 + 0) * 72 + s) * 2) = (bf16_t)(w0 & 0xffffu);
;                     *(LAS bf16_t*)(lds + HG_AM + ((tb0 + 1) * 72 + s) * 2) = (bf16_t)(w0 >> 16);
;                     *(LAS bf16_t*)(lds + HG_AM + ((tb0 + 2) * 72 + s) * 2) = (bf16_t)(w1 & 0xffffu);
;                     *(LAS bf16_t*)(lds + HG_AM + ((tb0 + 3) * 72 + s) * 2) = (bf16_t)(w1 >> 16);
;                 }
;             }
;             __syncthreads();
;             { const size_t or_ = row_base + (size_t)c * 64 + ti * 16 + fr;
; #pragma unroll
;               for (int jj = 0; jj < 4; ++jj) { cHG[jj] = *(const u32x2*)(HGt + or_ * DM + h * 128 + (dvh * 4 + jj) * 16 + 4 * fq); gn[jj] = *(const f32x4*)(a.in[7] + l * DM + h * 128 + (dvh * 4 + jj) * 16 + 4 * fq); } }
; #pragma unroll
;             for (int jj = 0; jj < 4; ++jj) oacc[jj] = (f32x4){0.f, 0.f, 0.f, 0.f};
; #pragma unroll
;             for (int k2 = 0; k2 < 2; ++k2) {
;                 const bf16x8 bv = lds_ld16(lds + HG_AM + ((ti * 16 + fr) * 72 + k2 * 32 + 8 * fq) * 2);
; #pragma unroll
;                 for (int jj = 0; jj < 4; ++jj) { const bf16x8 av = lds_ld16(lds + HG_VTT + (((dvh * 4 + jj) * 16 + fr) * 72 + k2 * 32 + 8 * fq) * 2); oacc[jj] = mfma16(av, bv, oacc[jj]); }
;             }
; #pragma unroll
;             for (int k4 = 0; k4 < 4; ++k4) {
	v_lshl_or_b32 v175, v89, 16, v80
	v_add_u32_e32 v89, s0, v96
	s_cselect_b64 s[0:1], -1, 0
	s_cmp_gt_i32 s9, 1
	s_cselect_b64 s[2:3], -1, 0
	s_cmp_gt_i32 s9, 2
	s_cselect_b64 s[4:5], -1, 0
	s_cmpk_lt_u32 s10, 0x80
	s_waitcnt vmcnt(1)
	v_lshl_or_b32 v39, v91, 16, v82
	s_waitcnt vmcnt(0)
	v_lshl_or_b32 v174, v92, 16, v83
	s_cselect_b64 s[36:37], -1, 0
	v_add_lshl_u32 v91, v50, s7, 1
	v_or_b32_e32 v50, s8, v42
	s_and_b32 s12, s8, 48
	v_bitop3_b32 v92, v48, 64, v65 bitop3:0x6c
	v_or_b32_e32 v48, s8, v47
	s_mul_i32 s8, s9, 0x880
	s_add_i32 s9, s8, 0x110
	v_add_lshl_u32 v68, s9, v41, 1
	v_add_lshl_u32 v69, s9, v43, 1
	s_add_i32 s9, s8, 0x220
	v_add_lshl_u32 v70, s9, v41, 1
	v_add_lshl_u32 v71, s9, v43, 1
	s_add_i32 s9, s8, 0x330
	v_lshl_or_b32 v182, v90, 16, v81
	v_add_lshl_u32 v80, s9, v41, 1
	v_add_lshl_u32 v81, s9, v43, 1
	s_add_i32 s9, s8, 0x440
	s_lshl_b32 s11, s6, 5
	s_ashr_i32 s6, s10, 2
	v_add_lshl_u32 v82, s9, v41, 1
	v_add_lshl_u32 v83, s9, v43, 1
	s_add_i32 s9, s8, 0x550
	s_and_b32 s38, s6, 0xffffffc0
	v_cmp_eq_u32_e64 s[6:7], 0, v49
	v_or_b32_e32 v49, s8, v41
	v_add_lshl_u32 v67, v43, s8, 1
	v_add_lshl_u32 v84, s9, v41, 1
	v_add_lshl_u32 v85, s9, v43, 1
	s_add_i32 s9, s8, 0x660
	s_addk_i32 s8, 0x770
	v_or_b32_e32 v188, s12, v47
	s_lshl_b32 s12, s12, 2
	v_add_lshl_u32 v87, s9, v43, 1
	v_add_lshl_u32 v134, s8, v43, 1
	v_mul_u32_u24_e32 v43, 0x88, v47
	s_add_i32 s12, s13, s12
	v_add_lshl_u32 v97, v50, v43, 1
	v_and_or_b32 v43, s11, 32, v47
	v_lshl_or_b32 v183, v86, 16, v78
	v_lshlrev_b32_e32 v51, 2, v50
	v_or_b32_e32 v63, s38, v47
	v_lshl_add_u32 v65, v47, 2, s12
	v_lshl_add_u32 v94, v188, 2, s13
	s_and_b32 s48, s10, 0xffffff00
	v_lshlrev_b32_e32 v66, 1, v49
	v_add_lshl_u32 v86, s9, v41, 1
	v_add_lshl_u32 v41, s8, v41, 1
	v_add_lshl_u32 v50, v52, v53, 1
	v_mul_u32_u24_e32 v49, 0x88, v43
	v_cmp_gt_i32_e64 s[8:9], v43, v54
	v_cmp_gt_i32_e64 s[10:11], v43, v55
	v_cmp_gt_i32_e64 s[12:13], v43, v56
	v_cmp_gt_i32_e64 s[14:15], v43, v57
	v_add_lshl_u32 v52, v58, v43, 1
	v_add_lshl_u32 v137, v59, v43, 1
	v_add_lshl_u32 v138, v60, v43, 1
	v_add_lshl_u32 v139, v61, v43, 1
	v_or_b32_e32 v43, 16, v43
	v_cmp_gt_i32_e64 s[16:17], v43, v54
	v_cmp_gt_i32_e64 s[18:19], v43, v55
	v_cmp_gt_i32_e64 s[20:21], v43, v56
	v_cmp_gt_i32_e64 s[22:23], v43, v57
	v_add_lshl_u32 v54, v58, v43, 1
	v_add_lshl_u32 v55, v59, v43, 1
	v_add_lshl_u32 v56, v60, v43, 1
	v_add_lshl_u32 v57, v61, v43, 1
	v_mul_lo_u32 v43, v63, s55
	v_or_b32_e32 v74, 32, v53
	v_mad_u32_u24 v62, v188, s55, v53
	v_lshlrev_b32_e32 v64, 6, v188
	v_add_lshl_u32 v100, v49, v53, 1
	s_ashr_i32 s39, s38, 31
	v_add_lshl_u32 v59, v43, v53, 1
	v_add_u32_e32 v49, 0x480, v43
	v_add_u32_e32 v61, 0x900, v43
	v_add_u32_e32 v73, 0xd80, v43
	v_add_lshl_u32 v154, v43, v74, 1
	v_mul_lo_u32 v43, v63, s49
	s_lshl_b64 s[34:35], s[34:35], 2
	v_lshlrev_b32_e32 v58, 1, v62
	v_add_lshl_u32 v60, v49, v53, 1
	v_add_lshl_u32 v153, v73, v53, 1
	v_add_lshl_u32 v155, v49, v74, 1
	v_add_lshl_u32 v157, v73, v74, 1
	v_add_lshl_u32 v62, v62, v64, 1
	v_add_u32_e32 v49, 0x880, v43
	v_add_u32_e32 v63, 0x1100, v43
	v_add_u32_e32 v64, 0x1980, v43
	v_or_b32_e32 v73, 64, v53
	s_add_u32 s30, s30, s34
	v_mul_lo_u32 v48, v48, s55
	v_add_lshl_u32 v109, v43, v73, 1
	v_add_lshl_u32 v110, v49, v73, 1
	v_add_lshl_u32 v111, v63, v73, 1
	v_add_lshl_u32 v112, v64, v73, 1
	v_or_b32_e32 v73, 0x60, v53
	s_addc_u32 s31, s31, s35
	s_lshl_b32 s34, s59, 2
	v_add_lshl_u32 v102, v49, v53, 1
	v_add_lshl_u32 v103, v63, v53, 1
	v_add_lshl_u32 v106, v49, v74, 1
	v_add_lshl_u32 v107, v63, v74, 1
	v_add_lshl_u32 v114, v49, v73, 1
	v_add_lshl_u32 v115, v63, v73, 1
	v_add_lshl_u32 v63, v48, v53, 1
	v_mov_b32_e32 v48, 0x480
	v_mov_b32_e32 v49, 0x900
	s_add_u32 s30, s30, s34
	v_mad_u32_u24 v48, v47, s55, v48
	v_mad_u32_u24 v49, v47, s55, v49
	s_addc_u32 s31, s31, 0
	v_add_lshl_u32 v113, v43, v73, 1
	v_add_lshl_u32 v116, v64, v73, 1
	v_add_lshl_u32 v159, v53, v48, 1
	v_add_lshl_u32 v160, v53, v49, 1
	v_mov_b32_e32 v73, 0xd80
	v_mov_b32_e32 v75, 0x1200
	v_mov_b32_e32 v76, 0x1680
	v_mov_b32_e32 v77, 0x1b00
	v_mov_b32_e32 v78, 0x1f80
	v_add_lshl_u32 v167, v74, v48, 1
	v_add_lshl_u32 v168, v74, v49, 1
	v_lshl_add_u64 v[48:49], v[44:45], 2, s[30:31]
	v_readlane_b32 s30, v253, 20
	v_add_lshl_u32 v101, v43, v53, 1
	v_add_lshl_u32 v105, v43, v74, 1
	v_mul_u32_u24_e32 v43, 0x48, v47
	v_mad_u32_u24 v73, v47, s55, v73
	v_mad_u32_u24 v75, v47, s55, v75
	v_mad_u32_u24 v76, v47, s55, v76
	v_mad_u32_u24 v77, v47, s55, v77
	v_mad_u32_u24 v47, v47, s55, v78
	s_add_u32 s30, s26, s30
	v_add_lshl_u32 v152, v61, v53, 1
	v_add_lshl_u32 v61, v61, v74, 1
	v_add_lshl_u32 v104, v64, v53, 1
	v_add_lshl_u32 v108, v64, v74, 1
	v_add_lshl_u32 v64, v53, v43, 1
	v_add_lshl_u32 v161, v53, v73, 1
	v_add_lshl_u32 v162, v53, v75, 1
	v_add_lshl_u32 v163, v53, v76, 1
	v_add_lshl_u32 v164, v53, v77, 1
	v_add_lshl_u32 v53, v53, v47, 1
	v_add_lshl_u32 v166, v74, v43, 1
	v_add_lshl_u32 v169, v74, v73, 1
	v_add_lshl_u32 v170, v74, v75, 1
	v_add_lshl_u32 v171, v74, v76, 1
	v_add_lshl_u32 v172, v74, v77, 1
	v_add_lshl_u32 v47, v74, v47, 1
	v_lshl_add_u64 v[74:75], s[38:39], 2, v[48:49]
	s_addc_u32 s31, s27, 0
	v_lshl_add_u64 v[48:49], s[52:53], 0, v[188:189]
	s_lshl_b64 s[26:27], s[38:39], 1
	v_lshlrev_b64 v[48:49], 11, v[48:49]
	s_add_u32 s26, s30, s26
	v_lshl_add_u64 v[44:45], v[44:45], 1, v[48:49]
	s_addc_u32 s27, s31, s27
	v_lshl_add_u64 v[76:77], s[26:27], 0, v[44:45]
	v_readlane_b32 s26, v253, 19
	v_add_u32_e32 v42, s38, v42
	s_add_u32 s24, s24, s26
	v_ashrrev_i32_e32 v43, 31, v42
	s_addc_u32 s25, s25, 0
	v_lshl_add_u64 v[42:43], v[42:43], 1, v[48:49]
	v_add_u32_e32 v140, 0x1100, v100
; #define LAS __attribute__((address_space(3)))
; __device__ __forceinline__ f32x4 mfma16(bf16x8 a, bf16x8 b, f32x4 c) { return __builtin_amdgcn_mfma_f32_16x16x32_bf16(a, b, c, 0, 0, 0); }
; template <bool FULL>
; __device__ __forceinline__ void hgrn_pass(int wv, const Args& a, int l, LAS unsigned char* lds, int item, bool dmy) {
;     ...
;         {
;             const f32x4 dd = *(const LAS f32x4*)(lds + HG_DV + (wid * 16 + 4 * fq) * 4);
; #pragma unroll
;             for (int j = 0; j < 8; ++j) sacc[j] = sacc[j] * dd;
; #pragma unroll
;             for (int k2 = 0; k2 < 2; ++k2) {
;                 const bf16x8 av = lds_ld16(lds + HG_KTT + ((wid * 16 + fr) * 72 + k2 * 32 + 8 * fq) * 2);
; #pragma unroll
;                 for (int j = 0; j < 8; ++j) { const bf16x8 bv = lds_ld16(lds + HG_VTT + ((j * 16 + fr) * 72 + k2 * 32 + 8 * fq) * 2); sacc[j] = mfma16(av, bv, sacc[j]); }
;             }
;         }
	v_lshl_add_u64 v[78:79], s[24:25], 0, v[42:43]
	v_readlane_b32 s24, v253, 25
	v_add_u32_e32 v90, s69, v96
	v_add_u32_e32 v96, s70, v96
	v_add_u32_e32 v98, 0x6600, v97
	v_add_u32_e32 v99, 0x7700, v97
	v_mov_b32_e32 v73, v72
	s_mov_b64 s[26:27], 0
	v_add_u32_e32 v119, 0, v66
	v_add_u32_e32 v120, 0, v67
	v_add_u32_e32 v121, 0, v68
	v_add_u32_e32 v122, 0, v69
	v_add_u32_e32 v123, 0, v70
	v_add_u32_e32 v124, 0, v71
	v_add_u32_e32 v125, 0, v80
	v_add_u32_e32 v126, 0, v81
	v_add_u32_e32 v127, 0, v82
	v_add_u32_e32 v128, 0, v83
	v_add_u32_e32 v129, 0, v84
	v_add_u32_e32 v130, 0, v85
	v_add_u32_e32 v131, 0, v86
	v_add_u32_e32 v132, 0, v87
	v_add_u32_e32 v133, 0, v41
	v_add_u32_e32 v134, 0, v134
	v_add_u32_e32 v135, 0, v50
	v_add_u32_e32 v136, s24, v52
	v_add_u32_e32 v137, s24, v137
	v_add_u32_e32 v138, s24, v138
	v_add_u32_e32 v139, s24, v139
	v_add_u32_e32 v140, 0, v140
	v_add_u32_e32 v141, s24, v54
	v_add_u32_e32 v142, s24, v55
	v_add_u32_e32 v143, s24, v56
	v_add_u32_e32 v144, s24, v57
	v_add_u32_e32 v145, s24, v58
	v_add_u32_e32 v146, 0, v62
	v_add_u32_e32 v147, s48, v65
	v_add_u32_e32 v148, 0, v63
	v_add_u32_e32 v149, 0, v51
	v_add_u32_e32 v150, s71, v59
	v_add_u32_e32 v151, s71, v60
	v_add_u32_e32 v152, s71, v152
	v_add_u32_e32 v153, s71, v153
	v_add_u32_e32 v154, s71, v154
	v_add_u32_e32 v155, s71, v155
	v_add_u32_e32 v156, s71, v61
	v_add_u32_e32 v157, s71, v157
	v_add_u32_e32 v158, s71, v64
	v_add_u32_e32 v159, s71, v159
	v_add_u32_e32 v160, s71, v160
	v_add_u32_e32 v161, s71, v161
	v_add_u32_e32 v162, s71, v162
	v_add_u32_e32 v163, s71, v163
	v_add_u32_e32 v164, s71, v164
	v_add_u32_e32 v165, s71, v53
	v_add_u32_e32 v166, s71, v166
	v_add_u32_e32 v167, s71, v167
	v_add_u32_e32 v168, s71, v168
	v_add_u32_e32 v169, s71, v169
	v_add_u32_e32 v170, s71, v170
	v_add_u32_e32 v171, s71, v171
	v_add_u32_e32 v172, s71, v172
	v_add_u32_e32 v173, s71, v47
	s_branch .LBB0_475
.LBB0_474:
	s_or_b64 exec, exec, s[24:25]
	s_waitcnt vmcnt(31)
	v_mov_b32_dpp v32, v184 quad_perm:[1,0,3,2] row_mask:0xf bank_mask:0xf
	v_perm_b32 v228, v32, v184, v118
	s_waitcnt vmcnt(30)
	v_mov_b32_dpp v32, v185 quad_perm:[1,0,3,2] row_mask:0xf bank_mask:0xf
	s_waitcnt vmcnt(29) lgkmcnt(0)
	v_mov_b32_dpp v33, v186 quad_perm:[1,0,3,2] row_mask:0xf bank_mask:0xf
	v_add_u32_e32 v184, 0x21000, v149
	v_perm_b32 v32, v32, v185, v118
	v_perm_b32 v181, v33, v186, v118
	ds_read_b128 v[184:187], v184
	s_waitcnt vmcnt(28)
	v_mov_b32_dpp v33, v200 quad_perm:[1,0,3,2] row_mask:0xf bank_mask:0xf
	v_perm_b32 v223, v33, v200, v118
	s_waitcnt vmcnt(27)
	v_mov_b32_dpp v33, v202 quad_perm:[1,0,3,2] row_mask:0xf bank_mask:0xf
	s_waitcnt vmcnt(26)
	v_mov_b32_dpp v34, v203 quad_perm:[1,0,3,2] row_mask:0xf bank_mask:0xf
	v_perm_b32 v33, v33, v202, v118
	v_perm_b32 v180, v34, v203, v118
	s_waitcnt lgkmcnt(0)
	v_pk_mul_f32 v[2:3], v[2:3], v[186:187]
	v_pk_mul_f32 v[0:1], v[0:1], v[184:185]
	v_pk_mul_f32 v[6:7], v[6:7], v[186:187]
	v_pk_mul_f32 v[4:5], v[4:5], v[184:185]
	v_pk_mul_f32 v[10:11], v[10:11], v[186:187]
	v_pk_mul_f32 v[8:9], v[8:9], v[184:185]
	v_pk_mul_f32 v[14:15], v[14:15], v[186:187]
	v_pk_mul_f32 v[12:13], v[12:13], v[184:185]
	v_pk_mul_f32 v[18:19], v[18:19], v[186:187]
	v_pk_mul_f32 v[16:17], v[16:17], v[184:185]
	v_pk_mul_f32 v[22:23], v[22:23], v[186:187]
	v_pk_mul_f32 v[20:21], v[20:21], v[184:185]
	v_pk_mul_f32 v[26:27], v[26:27], v[186:187]
	v_pk_mul_f32 v[24:25], v[24:25], v[184:185]
	v_pk_mul_f32 v[30:31], v[30:31], v[186:187]
	v_pk_mul_f32 v[28:29], v[28:29], v[184:185]
	ds_read_b128 v[184:187], v148 offset:52224
	ds_read_b128 v[200:203], v158
	s_waitcnt lgkmcnt(0)
	v_mfma_f32_16x16x32_bf16 v[0:3], v[184:187], v[200:203], v[0:3]
	ds_read_b128 v[200:203], v159
	s_waitcnt vmcnt(23)
	v_mov_b32_dpp v35, v208 quad_perm:[1,0,3,2] row_mask:0xf bank_mask:0xf
	s_waitcnt vmcnt(20)
	v_mov_b32_dpp v36, v214 quad_perm:[1,0,3,2] row_mask:0xf bank_mask:0xf
	s_waitcnt lgkmcnt(0)
	v_mfma_f32_16x16x32_bf16 v[4:7], v[184:187], v[200:203], v[4:7]
	ds_read_b128 v[200:203], v160
	s_waitcnt vmcnt(17)
	v_mov_b32_dpp v37, v220 quad_perm:[1,0,3,2] row_mask:0xf bank_mask:0xf
	s_waitcnt vmcnt(14)
	v_mov_b32_dpp v38, v244 quad_perm:[1,0,3,2] row_mask:0xf bank_mask:0xf
	s_waitcnt lgkmcnt(0)
	v_mfma_f32_16x16x32_bf16 v[8:11], v[184:187], v[200:203], v[8:11]
	ds_read_b128 v[200:203], v161
	s_waitcnt vmcnt(11)
	v_mov_b32_dpp v39, v229 quad_perm:[1,0,3,2] row_mask:0xf bank_mask:0xf
	v_mov_b32_dpp v34, v206 quad_perm:[1,0,3,2] row_mask:0xf bank_mask:0xf
	s_waitcnt lgkmcnt(0)
	v_mfma_f32_16x16x32_bf16 v[12:15], v[184:187], v[200:203], v[12:15]
	ds_read_b128 v[200:203], v162
	v_perm_b32 v179, v35, v208, v118
	v_mov_b32_dpp v35, v212 quad_perm:[1,0,3,2] row_mask:0xf bank_mask:0xf
	s_waitcnt lgkmcnt(0)
	v_mfma_f32_16x16x32_bf16 v[16:19], v[184:187], v[200:203], v[16:19]
	ds_read_b128 v[200:203], v163
	v_perm_b32 v178, v36, v214, v118
	v_mov_b32_dpp v36, v218 quad_perm:[1,0,3,2] row_mask:0xf bank_mask:0xf
	s_waitcnt lgkmcnt(0)
	v_mfma_f32_16x16x32_bf16 v[20:23], v[184:187], v[200:203], v[20:23]
	ds_read_b128 v[200:203], v164
	v_perm_b32 v177, v37, v220, v118
	v_mov_b32_dpp v37, v241 quad_perm:[1,0,3,2] row_mask:0xf bank_mask:0xf
	s_waitcnt lgkmcnt(0)
	v_mfma_f32_16x16x32_bf16 v[24:27], v[184:187], v[200:203], v[24:27]
	ds_read_b128 v[200:203], v165
	v_perm_b32 v176, v38, v244, v118
	v_mov_b32_dpp v38, v248 quad_perm:[1,0,3,2] row_mask:0xf bank_mask:0xf
	s_waitcnt lgkmcnt(0)
	v_mfma_f32_16x16x32_bf16 v[28:31], v[184:187], v[200:203], v[28:31]
	ds_read_b128 v[184:187], v148 offset:52288
	ds_read_b128 v[200:203], v166
	v_perm_b32 v175, v39, v229, v118
	s_waitcnt vmcnt(10)
; #define LAS __attribute__((address_space(3)))
; __device__ __forceinline__ float bflo(unsigned u) { return __uint_as_float(u << 16); }
; __device__ __forceinline__ float bfhi(unsigned u) { return __uint_as_float(u & 0xffff0000u); }
; __device__ __forceinline__ unsigned pk2(float lo, float hi) { f32x2 v = {lo, hi}; bf2_t b = __builtin_convertvector(v, bf2_t); return __builtin_bit_cast(unsigned, b); }
; __device__ __forceinline__ f32x4 mfma16(bf16x8 a, bf16x8 b, f32x4 c) { return __builtin_amdgcn_mfma_f32_16x16x32_bf16(a, b, c, 0, 0, 0); }
; template <bool FULL>
; __device__ __forceinline__ void hgrn_pass(int wv, const Args& a, int l, LAS unsigned char* lds, int item, bool dmy) {
;     ...
;         {
;             const f32x4 dd = *(const LAS f32x4*)(lds + HG_DV + (wid * 16 + 4 * fq) * 4);
; #pragma unroll
;             for (int j = 0; j < 8; ++j) sacc[j] = sacc[j] * dd;
; #pragma unroll
;             for (int k2 = 0; k2 < 2; ++k2) {
;                 const bf16x8 av = lds_ld16(lds + HG_KTT + ((wid * 16 + fr) * 72 + k2 * 32 + 8 * fq) * 2);
; #pragma unroll
;                 for (int j = 0; j < 8; ++j) { const bf16x8 bv = lds_ld16(lds + HG_VTT + ((j * 16 + fr) * 72 + k2 * 32 + 8 * fq) * 2); sacc[j] = mfma16(av, bv, sacc[j]); }
;             }
;         }
;         __syncthreads();
;         if (FULL) {
;             const int t = ti * 16 + fr;
;             const float tot = SSQP[t] + SSQP[64 + t];
;             const float rs = rsqrtf(tot * (1.f / 128.f) + EPS);
;             const size_t orow = row_base + (size_t)c * 64 + t;
; #pragma unroll
;             for (int jj = 0; jj < 4; ++jj) {
;                 const int dv0 = (dvh * 4 + jj) * 16 + 4 * fq;
;                 const u32x2 hg = cHG[jj];
;                 const float o0 = oacc[jj][0] * rs * gn[jj][0] * bflo(hg.x), o1 = oacc[jj][1] * rs * gn[jj][1] * bfhi(hg.x), o2 = oacc[jj][2] * rs * gn[jj][2] * bflo(hg.y), o3 = oacc[jj][3] * rs * gn[jj][3] * bfhi(hg.y);
;                 u32x2 w; w.x = pk2(o0, o1); w.y = pk2(o2, o3);
;                 *(u32x2*)(OA + orow * DM + h * 128 + dv0) = w;
;             }
;         }
; #pragma unroll
;         for (int i = 0; i < 8; ++i) { cHF[i] = nHF[i]; cHI[i] = nHI[i]; if (FULL) cHQ[i] = nHQ[i]; }
	v_mov_b32_dpp v39, v230 quad_perm:[1,0,3,2] row_mask:0xf bank_mask:0xf
	s_waitcnt lgkmcnt(0)
	v_mfma_f32_16x16x32_bf16 v[0:3], v[184:187], v[200:203], v[0:3]
	ds_read_b128 v[200:203], v167
	v_perm_b32 v222, v34, v206, v118
	v_mov_b32_dpp v34, v207 quad_perm:[1,0,3,2] row_mask:0xf bank_mask:0xf
	s_waitcnt lgkmcnt(0)
	v_mfma_f32_16x16x32_bf16 v[4:7], v[184:187], v[200:203], v[4:7]
	ds_read_b128 v[200:203], v168
	v_perm_b32 v236, v35, v212, v118
	v_mov_b32_dpp v35, v213 quad_perm:[1,0,3,2] row_mask:0xf bank_mask:0xf
	s_waitcnt lgkmcnt(0)
	v_mfma_f32_16x16x32_bf16 v[8:11], v[184:187], v[200:203], v[8:11]
	ds_read_b128 v[200:203], v169
	v_perm_b32 v242, v36, v218, v118
	v_mov_b32_dpp v36, v219 quad_perm:[1,0,3,2] row_mask:0xf bank_mask:0xf
	s_waitcnt lgkmcnt(0)
	v_mfma_f32_16x16x32_bf16 v[12:15], v[184:187], v[200:203], v[12:15]
	ds_read_b128 v[200:203], v170
	v_perm_b32 v199, v37, v241, v118
	v_mov_b32_dpp v37, v243 quad_perm:[1,0,3,2] row_mask:0xf bank_mask:0xf
	s_waitcnt lgkmcnt(0)
	v_mfma_f32_16x16x32_bf16 v[16:19], v[184:187], v[200:203], v[16:19]
	ds_read_b128 v[200:203], v171
	v_perm_b32 v183, v38, v248, v118
	v_mov_b32_dpp v38, v250 quad_perm:[1,0,3,2] row_mask:0xf bank_mask:0xf
	s_waitcnt lgkmcnt(0)
	v_mfma_f32_16x16x32_bf16 v[20:23], v[184:187], v[200:203], v[20:23]
	ds_read_b128 v[200:203], v172
	v_perm_b32 v182, v39, v230, v118
	s_waitcnt vmcnt(9)
	v_mov_b32_dpp v39, v231 quad_perm:[1,0,3,2] row_mask:0xf bank_mask:0xf
	s_waitcnt lgkmcnt(0)
	v_mfma_f32_16x16x32_bf16 v[24:27], v[184:187], v[200:203], v[24:27]
	ds_read_b128 v[200:203], v173
	s_waitcnt lgkmcnt(0)
	s_barrier
	v_mfma_f32_16x16x32_bf16 v[28:31], v[184:187], v[200:203], v[28:31]
	ds_read2st64_b32 v[184:185], v94 offset1:1
	s_waitcnt vmcnt(8)
	v_mov_b32_dpp v174, v232 quad_perm:[1,0,3,2] row_mask:0xf bank_mask:0xf
	v_perm_b32 v34, v34, v207, v118
	v_perm_b32 v35, v35, v213, v118
	v_perm_b32 v36, v36, v219, v118
	s_waitcnt lgkmcnt(0)
	v_add_f32_e32 v184, v184, v185
	v_fmamk_f32 v184, v184, 0x3c000000, v226
	v_cmp_gt_f32_e32 vcc, s33, v184
	v_mul_f32_e32 v185, 0x4b800000, v184
	v_perm_b32 v37, v37, v243, v118
	v_cndmask_b32_e32 v184, v184, v185, vcc
	v_rsq_f32_e32 v184, v184
	v_perm_b32 v38, v38, v250, v118
	v_perm_b32 v39, v39, v231, v118
	v_perm_b32 v174, v174, v232, v118
	v_mul_f32_e32 v185, 0x45800000, v184
	v_cndmask_b32_e32 v184, v184, v185, vcc
	v_pk_mul_f32 v[64:65], v[64:65], v[184:185] op_sel_hi:[1,0]
	v_pk_mul_f32 v[66:67], v[66:67], v[184:185] op_sel_hi:[1,0]
	s_waitcnt vmcnt(7)
	v_pk_mul_f32 v[64:65], v[68:69], v[64:65]
	s_waitcnt vmcnt(5)
	v_lshlrev_b32_e32 v68, 16, v86
	v_and_b32_e32 v69, 0xffff0000, v86
	v_pk_mul_f32 v[60:61], v[60:61], v[184:185] op_sel_hi:[1,0]
	v_pk_mul_f32 v[44:45], v[44:45], v[184:185] op_sel_hi:[1,0]
	v_pk_mul_f32 v[64:65], v[64:65], v[68:69]
	v_pk_mul_f32 v[66:67], v[70:71], v[66:67]
	v_lshlrev_b32_e32 v68, 16, v87
	v_and_b32_e32 v69, 0xffff0000, v87
	v_pk_mul_f32 v[56:57], v[56:57], v[60:61]
	s_waitcnt vmcnt(4)
	v_lshlrev_b32_e32 v60, 16, v84
	v_and_b32_e32 v61, 0xffff0000, v84
	v_pk_mul_f32 v[48:49], v[48:49], v[184:185] op_sel_hi:[1,0]
	s_waitcnt vmcnt(0)
	v_pk_mul_f32 v[40:41], v[40:41], v[44:45]
	v_lshlrev_b32_e32 v44, 16, v80
	v_and_b32_e32 v45, 0xffff0000, v80
	v_pk_mul_f32 v[66:67], v[66:67], v[68:69]
	v_pk_mul_f32 v[56:57], v[56:57], v[60:61]
	v_pk_mul_f32 v[60:61], v[62:63], v[184:185] op_sel_hi:[1,0]
	v_pk_mul_f32 v[48:49], v[52:53], v[48:49]
	v_lshlrev_b32_e32 v52, 16, v82
	v_and_b32_e32 v53, 0xffff0000, v82
	v_pk_mul_f32 v[50:51], v[50:51], v[184:185] op_sel_hi:[1,0]
	v_pk_mul_f32 v[40:41], v[40:41], v[44:45]
	v_pk_mul_f32 v[44:45], v[46:47], v[184:185] op_sel_hi:[1,0]
	v_cvt_pk_bf16_f32 v64, v64, v65
	v_cvt_pk_bf16_f32 v65, v66, v67
	v_lshl_add_u64 v[66:67], v[78:79], 0, s[26:27]
	v_pk_mul_f32 v[58:59], v[58:59], v[60:61]
	v_lshlrev_b32_e32 v60, 16, v85
	v_and_b32_e32 v61, 0xffff0000, v85
	v_pk_mul_f32 v[48:49], v[48:49], v[52:53]
	v_pk_mul_f32 v[50:51], v[54:55], v[50:51]
	v_lshlrev_b32_e32 v52, 16, v83
	v_and_b32_e32 v53, 0xffff0000, v83
	v_pk_mul_f32 v[42:43], v[42:43], v[44:45]
	v_lshlrev_b32_e32 v44, 16, v81
	v_and_b32_e32 v45, 0xffff0000, v81
	s_add_u32 s26, s26, 0x20000
	v_pk_mul_f32 v[58:59], v[58:59], v[60:61]
	v_pk_mul_f32 v[50:51], v[50:51], v[52:53]
	v_pk_mul_f32 v[42:43], v[42:43], v[44:45]
	s_addc_u32 s27, s27, 0
	s_add_i32 s47, s47, 64
	v_cvt_pk_bf16_f32 v56, v56, v57
	v_cvt_pk_bf16_f32 v57, v58, v59
	v_cvt_pk_bf16_f32 v48, v48, v49
	v_cvt_pk_bf16_f32 v49, v50, v51
	v_cvt_pk_bf16_f32 v40, v40, v41
	v_cvt_pk_bf16_f32 v41, v42, v43
	s_cmp_lg_u32 s26, 0x200000
	v_mbcnt_lo_u32_b32 v42, -1, 0
	v_mbcnt_hi_u32_b32 v42, -1, v42
	v_bfe_u32 v42, v42, 4, 1
	v_mul_u32_u24_e32 v42, 24, v42
	v_mov_b32_e32 v43, 0
	v_lshl_add_u64 v[66:67], v[42:43], 0, v[66:67]
	v_mov_b32_e32 v60, v64
	v_mov_b32_e32 v61, v65
	v_mov_b32_e32 v62, v56
	v_mov_b32_e32 v63, v57
	v_mov_b32_e32 v52, v48
	v_mov_b32_e32 v53, v49
	v_mov_b32_e32 v54, v40
	v_mov_b32_e32 v55, v41
	s_nop 1
	v_permlane16_swap_b32_e32 v60, v62
	v_permlane16_swap_b32_e32 v61, v63
	v_permlane16_swap_b32_e32 v52, v54
	v_permlane16_swap_b32_e32 v53, v55
	global_store_dwordx4 v[66:67], v[60:63], off
	global_store_dwordx4 v[66:67], v[52:55], off offset:64
	s_cbranch_scc0 .LBB0_479
; __device__ __forceinline__ float bflo(unsigned u) { return __uint_as_float(u << 16); }
; __device__ __forceinline__ float bfhi(unsigned u) { return __uint_as_float(u & 0xffff0000u); }
; __device__ __forceinline__ float fast_rcp(float x) { return __builtin_amdgcn_rcpf(x); }
; template <bool FULL>
; __device__ __forceinline__ void hgrn_pass(int wv, const Args& a, int l, LAS unsigned char* lds, int item, bool dmy) {
;     ...
;     for (int c = 0; c < 16; ++c) {
;         unsigned nHF[8], nHI[8], nHQ[8];
;         { const int cn = c < 15 ? c + 1 : 15; HG_LOAD(nHF, nHI, nHQ, cn); }
;         float cum[16], kk[16];
;         {
;             float run = 0.f;
; #pragma unroll
;             for (int i = 0; i < 16; ++i) {
;                 const float x = (i & 1) ? bfhi(cHF[i >> 1]) : bflo(cHF[i >> 1]);
;                 const float e = __expf(-x); const float sg = fast_rcp(1.f + e);
;                 const float f = lb + oml * sg;
;                 kk[i] = oml * (1.f - sg);
;                 run += __logf(f); cum[i] = run;
;             }
;             TOT[seg * 128 + ch] = run;
.LBB0_475:
	s_cmp_lg_u32 s26, 0x1e0000
	s_cselect_b32 s24, s47, 0x3c0
	s_add_u32 s24, s28, s24
	s_addc_u32 s25, s29, 0
	s_lshl_b64 s[34:35], s[24:25], 11
	s_add_u32 s24, s42, s34
	s_addc_u32 s25, s43, s35
	s_add_u32 s30, s45, s34
	s_addc_u32 s31, s46, s35
	s_add_u32 s34, s40, s34
	s_addc_u32 s35, s41, s35
	s_add_u32 s38, s24, 0x1000
	s_addc_u32 s39, s25, 0
	s_add_u32 s48, s30, 0x1000
	s_addc_u32 s49, s31, 0
	s_add_u32 s50, s34, 0x1000
	s_addc_u32 s51, s35, 0
	global_load_dword v184, v117, s[24:25]
	global_load_dword v185, v117, s[30:31]
	global_load_dword v186, v117, s[34:35]
	global_load_dword v200, v117, s[38:39]
	global_load_dword v202, v117, s[48:49]
	global_load_dword v203, v117, s[50:51]
	s_add_u32 s38, s24, 0x2000
	s_addc_u32 s39, s25, 0
	s_add_u32 s48, s30, 0x2000
	s_addc_u32 s49, s31, 0
	s_add_u32 s50, s34, 0x2000
	s_addc_u32 s51, s35, 0
	global_load_dword v206, v117, s[38:39]
	global_load_dword v207, v117, s[48:49]
	global_load_dword v208, v117, s[50:51]
	s_add_u32 s38, s24, 0x3000
	s_addc_u32 s39, s25, 0
	s_add_u32 s48, s30, 0x3000
	s_addc_u32 s49, s31, 0
	s_add_u32 s50, s34, 0x3000
	s_addc_u32 s51, s35, 0
	global_load_dword v212, v117, s[38:39]
	global_load_dword v213, v117, s[48:49]
	global_load_dword v214, v117, s[50:51]
	s_add_u32 s38, s24, 0x4000
	s_addc_u32 s39, s25, 0
	v_lshlrev_b32_e32 v40, 16, v228
	s_add_u32 s48, s30, 0x4000
	v_mul_f32_e32 v40, 0xbfb8aa3b, v40
	s_addc_u32 s49, s31, 0
	v_exp_f32_e32 v40, v40
	s_add_u32 s50, s34, 0x4000
	s_addc_u32 s51, s35, 0
	global_load_dword v218, v117, s[38:39]
	global_load_dword v219, v117, s[48:49]
	global_load_dword v220, v117, s[50:51]
	s_add_u32 s38, s24, 0x5000
	s_addc_u32 s39, s25, 0
	v_add_f32_e32 v40, 1.0, v40
	s_add_u32 s48, s30, 0x5000
	v_rcp_f32_e32 v40, v40
	s_addc_u32 s49, s31, 0
	s_add_u32 s50, s34, 0x5000
	s_addc_u32 s51, s35, 0
	global_load_dword v241, v117, s[38:39]
	global_load_dword v243, v117, s[48:49]
	global_load_dword v244, v117, s[50:51]
	s_add_u32 s38, s24, 0x6000
	v_fma_f32 v41, v72, v40, v88
	s_addc_u32 s39, s25, 0
	v_cmp_gt_f32_e32 vcc, s33, v41
	s_add_u32 s48, s30, 0x6000
	s_addc_u32 s49, s31, 0
	v_cndmask_b32_e64 v42, 0, 32, vcc
	v_ldexp_f32 v41, v41, v42
	s_add_u32 s50, s34, 0x6000
	v_log_f32_e32 v41, v41
	s_addc_u32 s51, s35, 0
	s_add_u32 s24, s24, 0x7000
	s_addc_u32 s25, s25, 0
	s_add_u32 s30, s30, 0x7000
	v_mul_f32_e32 v42, 0x3f317217, v41
	s_addc_u32 s31, s31, 0
	v_fma_f32 v42, v41, s93, -v42
	s_add_u32 s34, s34, 0x7000
	v_fmac_f32_e32 v42, 0x3377d1cf, v41
	global_load_dword v248, v117, s[38:39]
	global_load_dword v250, v117, s[48:49]
	global_load_dword v229, v117, s[50:51]
	s_addc_u32 s35, s35, 0
	global_load_dword v230, v117, s[24:25]
	global_load_dword v231, v117, s[30:31]
	global_load_dword v232, v117, s[34:35]
	v_fmac_f32_e32 v42, 0x3f317217, v41
	v_cmp_lt_f32_e64 s[24:25], |v41|, s92
	s_nop 1
	v_cndmask_b32_e64 v41, v41, v42, s[24:25]
	v_cndmask_b32_e32 v42, 0, v237, vcc
	v_sub_f32_e32 v41, v41, v42
	v_add_f32_e32 v60, 0, v41
	v_and_b32_e32 v41, 0xffff0000, v228
	v_mul_f32_e32 v41, 0xbfb8aa3b, v41
	v_exp_f32_e32 v41, v41
	s_nop 0
	v_add_f32_e32 v41, 1.0, v41
	v_rcp_f32_e32 v41, v41
	s_nop 0
	v_fma_f32 v42, v72, v41, v88
	v_cmp_gt_f32_e32 vcc, s33, v42
	s_nop 1
	v_cndmask_b32_e64 v43, 0, 32, vcc
	v_ldexp_f32 v42, v42, v43
	v_log_f32_e32 v42, v42
	s_nop 0
	v_mul_f32_e32 v43, 0x3f317217, v42
	v_fma_f32 v43, v42, s93, -v43
	v_fmac_f32_e32 v43, 0x3377d1cf, v42
	v_fmac_f32_e32 v43, 0x3f317217, v42
	v_cmp_lt_f32_e64 s[24:25], |v42|, s92
	s_nop 1
	v_cndmask_b32_e64 v42, v42, v43, s[24:25]
	v_cndmask_b32_e32 v43, 0, v237, vcc
	v_sub_f32_e32 v42, v42, v43
	v_add_f32_e32 v61, v42, v60
	v_lshlrev_b32_e32 v42, 16, v223
	v_mul_f32_e32 v42, 0xbfb8aa3b, v42
	v_exp_f32_e32 v42, v42
	s_nop 0
	v_add_f32_e32 v42, 1.0, v42
	v_rcp_f32_e32 v42, v42
	s_nop 0
	v_fma_f32 v43, v72, v42, v88
	v_cmp_gt_f32_e32 vcc, s33, v43
	s_nop 1
	v_cndmask_b32_e64 v44, 0, 32, vcc
	v_ldexp_f32 v43, v43, v44
	v_log_f32_e32 v43, v43
	s_nop 0
	v_mul_f32_e32 v44, 0x3f317217, v43
	v_fma_f32 v44, v43, s93, -v44
	v_fmac_f32_e32 v44, 0x3377d1cf, v43
	v_fmac_f32_e32 v44, 0x3f317217, v43
	v_cmp_lt_f32_e64 s[24:25], |v43|, s92
	s_nop 1
	v_cndmask_b32_e64 v43, v43, v44, s[24:25]
	v_cndmask_b32_e32 v44, 0, v237, vcc
	v_sub_f32_e32 v43, v43, v44
	v_add_f32_e32 v62, v43, v61
	v_and_b32_e32 v43, 0xffff0000, v223
	v_mul_f32_e32 v43, 0xbfb8aa3b, v43
	v_exp_f32_e32 v43, v43
	s_nop 0
	v_add_f32_e32 v43, 1.0, v43
	v_rcp_f32_e32 v43, v43
	s_nop 0
	v_fma_f32 v44, v72, v43, v88
	v_cmp_gt_f32_e32 vcc, s33, v44
	s_nop 1
	v_cndmask_b32_e64 v45, 0, 32, vcc
	v_ldexp_f32 v44, v44, v45
	v_log_f32_e32 v44, v44
	s_nop 0
	v_mul_f32_e32 v45, 0x3f317217, v44
	v_fma_f32 v45, v44, s93, -v45
	v_fmac_f32_e32 v45, 0x3377d1cf, v44
	v_fmac_f32_e32 v45, 0x3f317217, v44
	v_cmp_lt_f32_e64 s[24:25], |v44|, s92
	s_nop 1
	v_cndmask_b32_e64 v44, v44, v45, s[24:25]
	v_cndmask_b32_e32 v45, 0, v237, vcc
	v_sub_f32_e32 v44, v44, v45
	v_add_f32_e32 v63, v44, v62
	v_lshlrev_b32_e32 v44, 16, v222
	v_mul_f32_e32 v44, 0xbfb8aa3b, v44
	v_exp_f32_e32 v44, v44
	s_nop 0
	v_add_f32_e32 v44, 1.0, v44
	v_rcp_f32_e32 v44, v44
	s_nop 0
	v_fma_f32 v45, v72, v44, v88
	v_cmp_gt_f32_e32 vcc, s33, v45
	s_nop 1
	v_cndmask_b32_e64 v46, 0, 32, vcc
	v_ldexp_f32 v45, v45, v46
	v_log_f32_e32 v45, v45
	s_nop 0
	v_mul_f32_e32 v46, 0x3f317217, v45
	v_fma_f32 v46, v45, s93, -v46
	v_fmac_f32_e32 v46, 0x3377d1cf, v45
	v_fmac_f32_e32 v46, 0x3f317217, v45
	v_cmp_lt_f32_e64 s[24:25], |v45|, s92
	s_nop 1
	v_cndmask_b32_e64 v45, v45, v46, s[24:25]
	v_cndmask_b32_e32 v46, 0, v237, vcc
	v_sub_f32_e32 v45, v45, v46
	v_add_f32_e32 v64, v45, v63
	v_and_b32_e32 v45, 0xffff0000, v222
; __device__ __forceinline__ float bflo(unsigned u) { return __uint_as_float(u << 16); }
; __device__ __forceinline__ float bfhi(unsigned u) { return __uint_as_float(u & 0xffff0000u); }
; __device__ __forceinline__ float fast_rcp(float x) { return __builtin_amdgcn_rcpf(x); }
; template <bool FULL>
; __device__ __forceinline__ void hgrn_pass(int wv, const Args& a, int l, LAS unsigned char* lds, int item, bool dmy) {
;     ...
;             float run = 0.f;
; #pragma unroll
;             for (int i = 0; i < 16; ++i) {
;                 const float x = (i & 1) ? bfhi(cHF[i >> 1]) : bflo(cHF[i >> 1]);
;                 const float e = __expf(-x); const float sg = fast_rcp(1.f + e);
;                 const float f = lb + oml * sg;
;                 kk[i] = oml * (1.f - sg);
;                 run += __logf(f); cum[i] = run;
;             }
	v_mul_f32_e32 v45, 0xbfb8aa3b, v45
	v_exp_f32_e32 v45, v45
	s_nop 0
	v_add_f32_e32 v45, 1.0, v45
	v_rcp_f32_e32 v45, v45
	s_nop 0
	v_fma_f32 v46, v72, v45, v88
	v_cmp_gt_f32_e32 vcc, s33, v46
	s_nop 1
	v_cndmask_b32_e64 v47, 0, 32, vcc
	v_ldexp_f32 v46, v46, v47
	v_log_f32_e32 v46, v46
	s_nop 0
	v_mul_f32_e32 v47, 0x3f317217, v46
	v_fma_f32 v47, v46, s93, -v47
	v_fmac_f32_e32 v47, 0x3377d1cf, v46
	v_fmac_f32_e32 v47, 0x3f317217, v46
	v_cmp_lt_f32_e64 s[24:25], |v46|, s92
	s_nop 1
	v_cndmask_b32_e64 v46, v46, v47, s[24:25]
	v_cndmask_b32_e32 v47, 0, v237, vcc
	v_sub_f32_e32 v46, v46, v47
	v_add_f32_e32 v65, v46, v64
	v_lshlrev_b32_e32 v46, 16, v236
	v_mul_f32_e32 v46, 0xbfb8aa3b, v46
	v_exp_f32_e32 v46, v46
	s_nop 0
	v_add_f32_e32 v46, 1.0, v46
	v_rcp_f32_e32 v46, v46
	s_nop 0
	v_fma_f32 v47, v72, v46, v88
	v_cmp_gt_f32_e32 vcc, s33, v47
	s_nop 1
	v_cndmask_b32_e64 v48, 0, 32, vcc
	v_ldexp_f32 v47, v47, v48
	v_log_f32_e32 v47, v47
	s_nop 0
	v_mul_f32_e32 v48, 0x3f317217, v47
	v_fma_f32 v48, v47, s93, -v48
	v_fmac_f32_e32 v48, 0x3377d1cf, v47
	v_fmac_f32_e32 v48, 0x3f317217, v47
	v_cmp_lt_f32_e64 s[24:25], |v47|, s92
	s_nop 1
	v_cndmask_b32_e64 v47, v47, v48, s[24:25]
	v_cndmask_b32_e32 v48, 0, v237, vcc
	v_sub_f32_e32 v47, v47, v48
	v_add_f32_e32 v66, v47, v65
	v_and_b32_e32 v47, 0xffff0000, v236
	v_mul_f32_e32 v47, 0xbfb8aa3b, v47
	v_exp_f32_e32 v47, v47
	s_nop 0
	v_add_f32_e32 v47, 1.0, v47
	v_rcp_f32_e32 v47, v47
	s_nop 0
	v_fma_f32 v48, v72, v47, v88
	v_cmp_gt_f32_e32 vcc, s33, v48
	s_nop 1
	v_cndmask_b32_e64 v49, 0, 32, vcc
	v_ldexp_f32 v48, v48, v49
	v_log_f32_e32 v48, v48
	s_nop 0
	v_mul_f32_e32 v49, 0x3f317217, v48
	v_fma_f32 v49, v48, s93, -v49
	v_fmac_f32_e32 v49, 0x3377d1cf, v48
	v_fmac_f32_e32 v49, 0x3f317217, v48
	v_cmp_lt_f32_e64 s[24:25], |v48|, s92
	s_nop 1
	v_cndmask_b32_e64 v48, v48, v49, s[24:25]
	v_cndmask_b32_e32 v49, 0, v237, vcc
	v_sub_f32_e32 v48, v48, v49
	v_add_f32_e32 v67, v48, v66
	v_lshlrev_b32_e32 v48, 16, v242
	v_mul_f32_e32 v48, 0xbfb8aa3b, v48
	v_exp_f32_e32 v48, v48
	s_nop 0
	v_add_f32_e32 v48, 1.0, v48
	v_rcp_f32_e32 v48, v48
	s_nop 0
	v_fma_f32 v49, v72, v48, v88
	v_cmp_gt_f32_e32 vcc, s33, v49
	s_nop 1
	v_cndmask_b32_e64 v50, 0, 32, vcc
	v_ldexp_f32 v49, v49, v50
	v_log_f32_e32 v49, v49
	s_nop 0
	v_mul_f32_e32 v50, 0x3f317217, v49
	v_fma_f32 v50, v49, s93, -v50
	v_fmac_f32_e32 v50, 0x3377d1cf, v49
	v_fmac_f32_e32 v50, 0x3f317217, v49
	v_cmp_lt_f32_e64 s[24:25], |v49|, s92
	s_nop 1
	v_cndmask_b32_e64 v49, v49, v50, s[24:25]
	v_cndmask_b32_e32 v50, 0, v237, vcc
	v_sub_f32_e32 v49, v49, v50
	v_add_f32_e32 v68, v49, v67
	v_and_b32_e32 v49, 0xffff0000, v242
	v_mul_f32_e32 v49, 0xbfb8aa3b, v49
	v_exp_f32_e32 v49, v49
	s_nop 0
	v_add_f32_e32 v49, 1.0, v49
	v_rcp_f32_e32 v49, v49
	s_nop 0
	v_fma_f32 v50, v72, v49, v88
	v_cmp_gt_f32_e32 vcc, s33, v50
	s_nop 1
	v_cndmask_b32_e64 v51, 0, 32, vcc
	v_ldexp_f32 v50, v50, v51
	v_log_f32_e32 v50, v50
	s_nop 0
	v_mul_f32_e32 v51, 0x3f317217, v50
	v_fma_f32 v51, v50, s93, -v51
	v_fmac_f32_e32 v51, 0x3377d1cf, v50
	v_fmac_f32_e32 v51, 0x3f317217, v50
	v_cmp_lt_f32_e64 s[24:25], |v50|, s92
	s_nop 1
	v_cndmask_b32_e64 v50, v50, v51, s[24:25]
	v_cndmask_b32_e32 v51, 0, v237, vcc
	v_sub_f32_e32 v50, v50, v51
	v_add_f32_e32 v69, v50, v68
	v_lshlrev_b32_e32 v50, 16, v199
	v_mul_f32_e32 v50, 0xbfb8aa3b, v50
	v_exp_f32_e32 v50, v50
	s_nop 0
	v_add_f32_e32 v50, 1.0, v50
	v_rcp_f32_e32 v50, v50
	s_nop 0
	v_fma_f32 v51, v72, v50, v88
	v_cmp_gt_f32_e32 vcc, s33, v51
	s_nop 1
	v_cndmask_b32_e64 v52, 0, 32, vcc
	v_ldexp_f32 v51, v51, v52
	v_log_f32_e32 v51, v51
	s_nop 0
	v_mul_f32_e32 v52, 0x3f317217, v51
	v_fma_f32 v52, v51, s93, -v52
	v_fmac_f32_e32 v52, 0x3377d1cf, v51
	v_fmac_f32_e32 v52, 0x3f317217, v51
	v_cmp_lt_f32_e64 s[24:25], |v51|, s92
	s_nop 1
	v_cndmask_b32_e64 v51, v51, v52, s[24:25]
	v_cndmask_b32_e32 v52, 0, v237, vcc
; __device__ __forceinline__ float bflo(unsigned u) { return __uint_as_float(u << 16); }
; __device__ __forceinline__ float bfhi(unsigned u) { return __uint_as_float(u & 0xffff0000u); }
; __device__ __forceinline__ float fast_rcp(float x) { return __builtin_amdgcn_rcpf(x); }
; template <bool FULL>
; __device__ __forceinline__ void hgrn_pass(int wv, const Args& a, int l, LAS unsigned char* lds, int item, bool dmy) {
;     ...
;             for (int i = 0; i < 16; ++i) {
;                 const float x = (i & 1) ? bfhi(cHF[i >> 1]) : bflo(cHF[i >> 1]);
;                 const float e = __expf(-x); const float sg = fast_rcp(1.f + e);
;                 const float f = lb + oml * sg;
;                 kk[i] = oml * (1.f - sg);
;                 run += __logf(f); cum[i] = run;
;             }
;             TOT[seg * 128 + ch] = run;
;         }
;         __syncthreads();
;         float prefix = 0.f; const float t0 = TOT[ch], t1 = TOT[128 + ch], t2 = TOT[256 + ch], t3 = TOT[384 + ch];
;         if (seg >= 1) prefix += t0; if (seg >= 2) prefix += t1; if (seg >= 3) prefix += t2;
;         const float gmid = t0 + t1, glast = (t0 + t1) + (t2 + t3);
;         if (seg == 0) { DV[ch] = __expf(glast); gsum += glast; if (FULL) EM[ch] = __expf(gmid); }
	v_sub_f32_e32 v51, v51, v52
	v_add_f32_e32 v70, v51, v69
	v_and_b32_e32 v51, 0xffff0000, v199
	v_mul_f32_e32 v51, 0xbfb8aa3b, v51
	v_exp_f32_e32 v51, v51
	s_nop 0
	v_add_f32_e32 v51, 1.0, v51
	v_rcp_f32_e32 v51, v51
	s_nop 0
	v_fma_f32 v52, v72, v51, v88
	v_cmp_gt_f32_e32 vcc, s33, v52
	s_nop 1
	v_cndmask_b32_e64 v53, 0, 32, vcc
	v_ldexp_f32 v52, v52, v53
	v_log_f32_e32 v52, v52
	s_nop 0
	v_mul_f32_e32 v53, 0x3f317217, v52
	v_fma_f32 v53, v52, s93, -v53
	v_fmac_f32_e32 v53, 0x3377d1cf, v52
	v_fmac_f32_e32 v53, 0x3f317217, v52
	v_cmp_lt_f32_e64 s[24:25], |v52|, s92
	s_nop 1
	v_cndmask_b32_e64 v52, v52, v53, s[24:25]
	v_cndmask_b32_e32 v53, 0, v237, vcc
	v_sub_f32_e32 v52, v52, v53
	v_add_f32_e32 v71, v52, v70
	v_lshlrev_b32_e32 v52, 16, v183
	v_mul_f32_e32 v52, 0xbfb8aa3b, v52
	v_exp_f32_e32 v52, v52
	s_nop 0
	v_add_f32_e32 v52, 1.0, v52
	v_rcp_f32_e32 v52, v52
	s_nop 0
	v_fma_f32 v53, v72, v52, v88
	v_cmp_gt_f32_e32 vcc, s33, v53
	s_nop 1
	v_cndmask_b32_e64 v54, 0, 32, vcc
	v_ldexp_f32 v53, v53, v54
	v_log_f32_e32 v53, v53
	s_nop 0
	v_mul_f32_e32 v54, 0x3f317217, v53
	v_fma_f32 v54, v53, s93, -v54
	v_fmac_f32_e32 v54, 0x3377d1cf, v53
	v_fmac_f32_e32 v54, 0x3f317217, v53
	v_cmp_lt_f32_e64 s[24:25], |v53|, s92
	s_nop 1
	v_cndmask_b32_e64 v53, v53, v54, s[24:25]
	v_cndmask_b32_e32 v54, 0, v237, vcc
	v_sub_f32_e32 v53, v53, v54
	v_add_f32_e32 v80, v53, v71
	v_and_b32_e32 v53, 0xffff0000, v183
	v_mul_f32_e32 v53, 0xbfb8aa3b, v53
	v_exp_f32_e32 v53, v53
	s_nop 0
	v_add_f32_e32 v53, 1.0, v53
	v_rcp_f32_e32 v53, v53
	s_nop 0
	v_fma_f32 v54, v72, v53, v88
	v_cmp_gt_f32_e32 vcc, s33, v54
	s_nop 1
	v_cndmask_b32_e64 v55, 0, 32, vcc
	v_ldexp_f32 v54, v54, v55
	v_log_f32_e32 v54, v54
	s_nop 0
	v_mul_f32_e32 v55, 0x3f317217, v54
	v_fma_f32 v55, v54, s93, -v55
	v_fmac_f32_e32 v55, 0x3377d1cf, v54
	v_fmac_f32_e32 v55, 0x3f317217, v54
	v_cmp_lt_f32_e64 s[24:25], |v54|, s92
	s_nop 1
	v_cndmask_b32_e64 v54, v54, v55, s[24:25]
	v_cndmask_b32_e32 v55, 0, v237, vcc
	v_sub_f32_e32 v54, v54, v55
	v_add_f32_e32 v81, v54, v80
	v_lshlrev_b32_e32 v54, 16, v182
	v_mul_f32_e32 v54, 0xbfb8aa3b, v54
	v_exp_f32_e32 v54, v54
	s_nop 0
	v_add_f32_e32 v54, 1.0, v54
	v_rcp_f32_e32 v54, v54
	s_nop 0
	v_fma_f32 v55, v72, v54, v88
	v_cmp_gt_f32_e32 vcc, s33, v55
	s_nop 1
	v_cndmask_b32_e64 v56, 0, 32, vcc
	v_ldexp_f32 v55, v55, v56
	v_log_f32_e32 v55, v55
	s_nop 0
	v_mul_f32_e32 v56, 0x3f317217, v55
	v_fma_f32 v56, v55, s93, -v56
	v_fmac_f32_e32 v56, 0x3377d1cf, v55
	v_fmac_f32_e32 v56, 0x3f317217, v55
	v_cmp_lt_f32_e64 s[24:25], |v55|, s92
	s_nop 1
	v_cndmask_b32_e64 v55, v55, v56, s[24:25]
	v_cndmask_b32_e32 v56, 0, v237, vcc
	v_sub_f32_e32 v55, v55, v56
	v_add_f32_e32 v82, v55, v81
	v_and_b32_e32 v55, 0xffff0000, v182
	v_mul_f32_e32 v55, 0xbfb8aa3b, v55
	v_exp_f32_e32 v55, v55
	s_nop 0
	v_add_f32_e32 v55, 1.0, v55
	v_rcp_f32_e32 v55, v55
	s_nop 0
	v_fma_f32 v56, v72, v55, v88
	v_cmp_gt_f32_e32 vcc, s33, v56
	s_nop 1
	v_cndmask_b32_e64 v57, 0, 32, vcc
	v_ldexp_f32 v56, v56, v57
	v_log_f32_e32 v56, v56
	s_nop 0
	v_mul_f32_e32 v57, 0x3f317217, v56
	v_fma_f32 v57, v56, s93, -v57
	v_fmac_f32_e32 v57, 0x3377d1cf, v56
	v_fmac_f32_e32 v57, 0x3f317217, v56
	v_cmp_lt_f32_e64 s[24:25], |v56|, s92
	s_nop 1
	v_cndmask_b32_e64 v56, v56, v57, s[24:25]
	v_cndmask_b32_e32 v57, 0, v237, vcc
	v_sub_f32_e32 v56, v56, v57
	v_add_f32_e32 v83, v56, v82
	ds_write_b32 v89, v83
	s_waitcnt lgkmcnt(0)
	s_barrier
	ds_read2st64_b32 v[58:59], v90 offset1:2
	ds_read2st64_b32 v[56:57], v90 offset0:4 offset1:6
	s_andn2_b64 vcc, exec, s[36:37]
	s_waitcnt lgkmcnt(1)
	v_add_f32_e32 v84, v58, v59
	s_waitcnt lgkmcnt(0)
	v_add_f32_e32 v57, v56, v57
	v_add_f32_e32 v57, v84, v57
	s_cbranch_vccnz .LBB0_477
	v_mul_f32_e32 v85, 0x3fb8aa3b, v57
	v_exp_f32_e32 v85, v85
	v_mul_f32_e32 v86, 0x3fb8aa3b, v84
	v_exp_f32_e32 v86, v86
	ds_write_b32 v96, v85
	ds_write_b32 v95, v86 offset:34816
